# attention near tiles: T5 bias/mask table values enter through the C operand of the first two QK MFMAs (loaded at step top) instead of 32 VALU adds; near tiles then share the far-tile post-QK code
# speedup vs baseline: 1.0089x; 1.0004x over previous
; #define SBAR() __builtin_amdgcn_sched_barrier(0)
; #define VRD(i) do { if constexpr (VAR & 2) break; lo[(i) & 3] = vtr(vb + v_rd_off((i) >> 2, (i) & 3, 0)); hv[(i) & 3] = vtr(vb + v_rd_off((i) >> 2, (i) & 3, 1)); } while (0)
; template <int VAR> ...
;     ...
;     float ps = 0.f;
;     if constexpr (VAR & 4) { ka[0] = qr[0]; ka[1] = qr[1]; ka[2] = qr[2]; ka[3] = qr[3]; kb[0] = qr[0]; kb[1] = qr[1]; kb[2] = qr[2]; kb[3] = qr[3]; }
;     ka[0] = kp[0]; kb[0] = kp[1]; ka[1] = kp[2]; kb[1] = kp[3]; if (dk) glds16(gk, lk); SBAR();
;     { const f32x16 z = f32x16{};
;       QKM(x0, ka[0], qr[0], z);  SUM4(y0, 0); PKA(y0, 0);       SBAR();
;       QKM(x1, kb[0], qr[0], z);  SUM4(y0, 4); PKB(y0, 4, pa0);  KRD(2); if (dv) glds16(gv, lv); SBAR(); }
;     QKM(x0, ka[1], qr[1], x0); SUM4(y0, 8); PKA(y0, 8);       SBAR();
;     QKM(x1, kb[1], qr[1], x1); SUM4(y0, 12); PKB(y0, 12, pa1); KRD(3); if (dv) glds16(gv + 8192, lv + 8192); SBAR();
;     QKM(x0, ka[2], qr[2], x0); SUM4(y1, 0); PKA(y1, 0);       SBAR();
;     QKM(x1, kb[2], qr[2], x1); SUM4(y1, 4); PKB(y1, 4, pa2);  SBAR();
;     QKM(x0, ka[3], qr[3], x0); SUM4(y1, 8); PKA(y1, 8);       SBAR();
;     QKM(x1, kb[3], qr[3], x1); SUM4(y1, 12); PKB(y1, 12, pa3); VRD(0); VRD(1); SBAR();
;     VRD(2); VRD(3); SBAR();
;     if (near) {
;         float tA[4], uA[4], tB[4], uB[4];
;     ...
;         TLD(tA, uA, 0); SBAR(); TLD(tB, uB, 1); SBAR();
;         asm volatile("s_nop 15\n\ts_nop 7" : "+v"(x0), "+v"(x1));
;         TAD(tA, uA, 0); SBAR(); TLD(tA, uA, 2); SBAR(); TAD(tB, uB, 1); SBAR(); TLD(tB, uB, 3); SBAR(); TAD(tA, uA, 2); SBAR(); TAD(tB, uB, 3);
;     ...
;     } else if (__builtin_expect(shift != 0.f, 0)) {
;         asm volatile("s_nop 15\n\ts_nop 7" : "+v"(x0), "+v"(x1));
; #pragma unroll
;         for (int r = 0; r < 16; ++r) { asm volatile("v_sub_f32 %0, %0, %1" : "+v"(x0[r]) : "v"(shift)); asm volatile("v_sub_f32 %0, %0, %1" : "+v"(x1[r]) : "v"(shift)); }
;     }
;     SBAR();
;     ...
;     GAPB(0, pa0); GAPB(1, pa1); GAPB(2, pa2); GAPB(3, pa3); GAPB(4, pa0); GAPB(5, pa1); GAPB(6, pa2); GAPB(7, pa3);
;     GAPB(8, pa0); GAPB(9, pa1); GAPB(10, pa2); GAPB(11, pa3);
;     if (wv == 3) asm volatile("s_waitcnt vmcnt(3)" ::: "memory"); else if (wv == 2) asm volatile("s_waitcnt vmcnt(2)" ::: "memory"); else asm volatile("s_waitcnt vmcnt(0)" ::: "memory");
;     asm volatile("s_waitcnt lgkmcnt(0)\n\ts_barrier" ::: "memory");
.LBB0_356:
	s_lshl_b32 s0, s67, 13
	s_lshl_b32 s1, s86, 14
	s_add_i32 s90, s20, 1
	s_add_i32 s0, s0, s88
	s_add_i32 s66, s1, s87
	v_lshl_add_u64 v[4:5], v[206:207], 0, s[44:45]
	s_mov_b32 m0, s0
	s_lshl_b32 s92, s91, 13
	global_load_lds_dwordx4 v[4:5], off
	v_add_u32_e32 v12, s92, v215
	s_sub_i32 s2, s89, 64
	s_cmp_le_i32 s2, s85
	s_cselect_b64 s[100:101], s[4:5], 0
	s_cbranch_scc0 .Lp2n_near1
	s_waitcnt lgkmcnt(3)
	v_mfma_f32_32x32x16_bf16 v[130:145], v[174:177], v[146:149], 0
	v_add_f32_e32 v4, v82, v83
	v_add_f32_e32 v5, v84, v85
	v_add_f32_e32 v6, v4, v5
	v_cvt_pk_bf16_f32 v4, v82, v83
	v_cvt_pk_bf16_f32 v5, v84, v85
	v_add_f32_e32 v7, v86, v87
	v_add_f32_e32 v8, v88, v89
	s_waitcnt lgkmcnt(2)
	v_mfma_f32_32x32x16_bf16 v[114:129], v[170:173], v[146:149], 0
.Lp2n_join1:
	v_add_f32_e32 v7, v7, v8
	v_add_f32_e32 v8, v7, v6
	v_cvt_pk_bf16_f32 v6, v86, v87
	v_cvt_pk_bf16_f32 v7, v88, v89
	v_add_u32_e32 v9, v12, v218
	s_mov_b32 m0, s66
	ds_read_b128 v[14:17], v9 offset:49152
	ds_read_b128 v[86:89], v9 offset:53248
	global_load_lds_dwordx4 v[208:209], off
	s_waitcnt lgkmcnt(3)
	v_mfma_f32_32x32x16_bf16 v[130:145], v[166:169], v[150:153], v[130:145]
	v_add_f32_e32 v9, v90, v91
	v_add_f32_e32 v10, v92, v93
	v_add_f32_e32 v9, v9, v10
	v_add_f32_e32 v10, v9, v8
	v_cvt_pk_bf16_f32 v8, v90, v91
	v_cvt_pk_bf16_f32 v9, v92, v93
	v_add_f32_e32 v11, v94, v95
	v_add_f32_e32 v13, v96, v97
	s_waitcnt lgkmcnt(2)
	v_mfma_f32_32x32x16_bf16 v[114:129], v[162:165], v[150:153], v[114:129]
	v_add_f32_e32 v11, v11, v13
	v_add_f32_e32 v13, v11, v10
	v_cvt_pk_bf16_f32 v10, v94, v95
	v_cvt_pk_bf16_f32 v11, v96, v97
	v_add_u32_e32 v12, v12, v219
	ds_read_b128 v[90:93], v12 offset:49152
	ds_read_b128 v[82:85], v12 offset:53248
	s_add_i32 m0, s66, 0x2000
	v_lshl_add_u64 v[94:95], v[208:209], 0, s[22:23]
	global_load_lds_dwordx4 v[94:95], off
	s_lshl_b32 s2, s67, 14
	s_waitcnt lgkmcnt(3)
	v_mfma_f32_32x32x16_bf16 v[130:145], v[14:17], v[154:157], v[130:145]
	v_add_f32_e32 v12, v98, v99
	v_add_f32_e32 v94, v100, v101
	v_add_f32_e32 v12, v12, v94
	v_add_f32_e32 v94, v12, v13
	v_cvt_pk_bf16_f32 v12, v98, v99
	v_cvt_pk_bf16_f32 v13, v100, v101
	s_waitcnt lgkmcnt(2)
	v_mfma_f32_32x32x16_bf16 v[114:129], v[86:89], v[154:157], v[114:129]
	v_add_f32_e32 v14, v102, v103
	v_add_f32_e32 v15, v104, v105
	v_add_f32_e32 v14, v14, v15
	v_add_f32_e32 v16, v14, v94
	v_cvt_pk_bf16_f32 v14, v102, v103
	v_cvt_pk_bf16_f32 v15, v104, v105
	s_waitcnt lgkmcnt(1)
	v_mfma_f32_32x32x16_bf16 v[130:145], v[90:93], v[158:161], v[130:145]
	v_add_f32_e32 v17, v106, v107
	v_add_f32_e32 v86, v108, v109
	v_add_f32_e32 v17, v17, v86
	v_add_f32_e32 v16, v17, v16
	v_cvt_pk_bf16_f32 v178, v106, v107
	v_cvt_pk_bf16_f32 v179, v108, v109
	v_add_f32_e32 v17, v110, v111
	v_add_f32_e32 v86, v112, v113
	v_add_f32_e32 v17, v17, v86
	v_add_f32_e32 v229, v17, v16
	v_cvt_pk_bf16_f32 v180, v110, v111
	v_cvt_pk_bf16_f32 v181, v112, v113
	v_add_u32_e32 v16, s2, v214
	s_waitcnt lgkmcnt(0)
	v_mfma_f32_32x32x16_bf16 v[114:129], v[82:85], v[158:161], v[114:129]
	ds_read_b64_tr_b16 v[174:175], v16
	ds_read_b64_tr_b16 v[176:177], v16 offset:256
	ds_read_b64_tr_b16 v[170:171], v16 offset:4096
	ds_read_b64_tr_b16 v[172:173], v16 offset:4352
	ds_read_b64_tr_b16 v[166:167], v16 offset:8192
	ds_read_b64_tr_b16 v[168:169], v16 offset:8448
	ds_read_b64_tr_b16 v[162:163], v16 offset:12288
	ds_read_b64_tr_b16 v[164:165], v16 offset:12544
	v_mov_b64_e32 v[82:83], v[130:131]
	s_and_b64 vcc, exec, s[100:101]
	v_mov_b64_e32 v[84:85], v[132:133]
	v_mov_b64_e32 v[86:87], v[134:135]
	v_mov_b64_e32 v[88:89], v[136:137]
	v_mov_b64_e32 v[90:91], v[138:139]
	v_mov_b64_e32 v[92:93], v[140:141]
	v_mov_b64_e32 v[94:95], v[142:143]
	v_mov_b64_e32 v[96:97], v[144:145]
	s_cbranch_vccnz .Lp2t_shift1
.LBB0_367:
	s_waitcnt lgkmcnt(6)
	v_mfma_f32_32x32x16_bf16 v[66:81], v[4:7], v[174:177], v[66:81]
	v_exp_f32_e32 v82, v82
	v_exp_f32_e32 v114, v114
	ds_read_b64_tr_b16 v[98:99], v16 offset:512
	ds_read_b64_tr_b16 v[100:101], v16 offset:768
	s_waitcnt lgkmcnt(6)
	v_mfma_f32_32x32x16_bf16 v[66:81], v[8:11], v[170:173], v[66:81]
	v_exp_f32_e32 v83, v83
	v_exp_f32_e32 v115, v115
	ds_read_b64_tr_b16 v[102:103], v16 offset:4608
	ds_read_b64_tr_b16 v[104:105], v16 offset:4864
	s_waitcnt lgkmcnt(6)
	v_mfma_f32_32x32x16_bf16 v[66:81], v[12:15], v[166:169], v[66:81]
	v_exp_f32_e32 v84, v84
	v_exp_f32_e32 v116, v116
	ds_read_b64_tr_b16 v[106:107], v16 offset:8704
	ds_read_b64_tr_b16 v[108:109], v16 offset:8960
	s_waitcnt lgkmcnt(6)
	v_mfma_f32_32x32x16_bf16 v[66:81], v[178:181], v[162:165], v[66:81]
	v_exp_f32_e32 v85, v85
	v_exp_f32_e32 v117, v117
	ds_read_b64_tr_b16 v[110:111], v16 offset:12800
	ds_read_b64_tr_b16 v[112:113], v16 offset:13056
	s_waitcnt lgkmcnt(6)
	v_mfma_f32_32x32x16_bf16 v[50:65], v[4:7], v[98:101], v[50:65]
	v_exp_f32_e32 v86, v86
	v_exp_f32_e32 v118, v118
	ds_read_b64_tr_b16 v[130:131], v16 offset:1024
	ds_read_b64_tr_b16 v[132:133], v16 offset:1280
	s_waitcnt lgkmcnt(6)
	v_mfma_f32_32x32x16_bf16 v[50:65], v[8:11], v[102:105], v[50:65]
	v_exp_f32_e32 v87, v87
	v_exp_f32_e32 v119, v119
	ds_read_b64_tr_b16 v[134:135], v16 offset:5120
	ds_read_b64_tr_b16 v[136:137], v16 offset:5376
	s_waitcnt lgkmcnt(6)
	v_mfma_f32_32x32x16_bf16 v[50:65], v[12:15], v[106:109], v[50:65]
	v_exp_f32_e32 v88, v88
	v_exp_f32_e32 v120, v120
	ds_read_b64_tr_b16 v[138:139], v16 offset:9216
	ds_read_b64_tr_b16 v[140:141], v16 offset:9472
	s_waitcnt lgkmcnt(6)
	v_mfma_f32_32x32x16_bf16 v[50:65], v[178:181], v[110:113], v[50:65]
	v_exp_f32_e32 v89, v89
	v_exp_f32_e32 v121, v121
	ds_read_b64_tr_b16 v[142:143], v16 offset:13312
	ds_read_b64_tr_b16 v[144:145], v16 offset:13568
	s_waitcnt lgkmcnt(6)
	v_mfma_f32_32x32x16_bf16 v[34:49], v[4:7], v[130:133], v[34:49]
	v_exp_f32_e32 v90, v90
	v_exp_f32_e32 v122, v122
	ds_read_b64_tr_b16 v[98:99], v16 offset:1536
	ds_read_b64_tr_b16 v[100:101], v16 offset:1792
	s_waitcnt lgkmcnt(6)
	v_mfma_f32_32x32x16_bf16 v[34:49], v[8:11], v[134:137], v[34:49]
	v_exp_f32_e32 v91, v91
	v_exp_f32_e32 v123, v123
	ds_read_b64_tr_b16 v[102:103], v16 offset:5632
	ds_read_b64_tr_b16 v[104:105], v16 offset:5888
	s_waitcnt lgkmcnt(6)
	v_mfma_f32_32x32x16_bf16 v[34:49], v[12:15], v[138:141], v[34:49]
	v_exp_f32_e32 v92, v92
	v_exp_f32_e32 v124, v124
	ds_read_b64_tr_b16 v[106:107], v16 offset:9728
	ds_read_b64_tr_b16 v[108:109], v16 offset:9984
	s_waitcnt lgkmcnt(6)
	v_mfma_f32_32x32x16_bf16 v[34:49], v[178:181], v[142:145], v[34:49]
	v_exp_f32_e32 v93, v93
	v_exp_f32_e32 v125, v125
	ds_read_b64_tr_b16 v[110:111], v16 offset:13824
	ds_read_b64_tr_b16 v[112:113], v16 offset:14080
	s_waitcnt vmcnt(3)
	v_lshl_add_u32 v182, s86, 13, v215
	s_waitcnt lgkmcnt(0)
	s_barrier
; #define SBAR() __builtin_amdgcn_sched_barrier(0)
; template <int VAR> ...
;     ...
;     float ps = 0.f;
;     if constexpr (VAR & 4) { ka[0] = qr[0]; ka[1] = qr[1]; ka[2] = qr[2]; ka[3] = qr[3]; kb[0] = qr[0]; kb[1] = qr[1]; kb[2] = qr[2]; kb[3] = qr[3]; }
;     ka[0] = kp[0]; kb[0] = kp[1]; ka[1] = kp[2]; kb[1] = kp[3]; if (dk) glds16(gk, lk); SBAR();
;     { const f32x16 z = f32x16{};
;       QKM(x0, ka[0], qr[0], z);  SUM4(y0, 0); PKA(y0, 0);       SBAR();
;       QKM(x1, kb[0], qr[0], z);  SUM4(y0, 4); PKB(y0, 4, pa0);  KRD(2); if (dv) glds16(gv, lv); SBAR(); }
;     QKM(x0, ka[1], qr[1], x0); SUM4(y0, 8); PKA(y0, 8);       SBAR();
;     QKM(x1, kb[1], qr[1], x1); SUM4(y0, 12); PKB(y0, 12, pa1); KRD(3); if (dv) glds16(gv + 8192, lv + 8192); SBAR();
;     QKM(x0, ka[2], qr[2], x0); SUM4(y1, 0); PKA(y1, 0);       SBAR();
;     QKM(x1, kb[2], qr[2], x1); SUM4(y1, 4); PKB(y1, 4, pa2);  SBAR();
;     QKM(x0, ka[3], qr[3], x0); SUM4(y1, 8); PKA(y1, 8);       SBAR();
;     QKM(x1, kb[3], qr[3], x1); SUM4(y1, 12); PKB(y1, 12, pa3); VRD(0); VRD(1); SBAR();
;     VRD(2); VRD(3); SBAR();
;     if (near) {
;         float tA[4], uA[4], tB[4], uB[4];
;     ...
;         TLD(tA, uA, 0); SBAR(); TLD(tB, uB, 1); SBAR();
;         asm volatile("s_nop 15\n\ts_nop 7" : "+v"(x0), "+v"(x1));
;         TAD(tA, uA, 0); SBAR(); TLD(tA, uA, 2); SBAR(); TAD(tB, uB, 1); SBAR(); TLD(tB, uB, 3); SBAR(); TAD(tA, uA, 2); SBAR(); TAD(tB, uB, 3);
;     ...
;     } else if (__builtin_expect(shift != 0.f, 0)) {
;         asm volatile("s_nop 15\n\ts_nop 7" : "+v"(x0), "+v"(x1));
; #pragma unroll
;         for (int r = 0; r < 16; ++r) { asm volatile("v_sub_f32 %0, %0, %1" : "+v"(x0[r]) : "v"(shift)); asm volatile("v_sub_f32 %0, %0, %1" : "+v"(x1[r]) : "v"(shift)); }
;     }
;     SBAR();
;     ...
;     GAPB(0, pa0); GAPB(1, pa1); GAPB(2, pa2); GAPB(3, pa3); GAPB(4, pa0); GAPB(5, pa1); GAPB(6, pa2); GAPB(7, pa3);
;     GAPB(8, pa0); GAPB(9, pa1); GAPB(10, pa2); GAPB(11, pa3);
;     if (wv == 3) asm volatile("s_waitcnt vmcnt(3)" ::: "memory"); else if (wv == 2) asm volatile("s_waitcnt vmcnt(2)" ::: "memory"); else asm volatile("s_waitcnt vmcnt(0)" ::: "memory");
;     asm volatile("s_waitcnt lgkmcnt(0)\n\ts_barrier" ::: "memory");
;     if (pre) { const char* a0_ = Kn + (((0 + hi) ^ sw) << 4); const char* a1_ = Kn + (((2 + hi) ^ sw) << 4);
	v_add_u32_e32 v16, v182, v216
	v_add_u32_e32 v17, v182, v217
	ds_read_b128 v[174:177], v16 offset:49152
	ds_read_b128 v[170:173], v16 offset:53248
	ds_read_b128 v[166:169], v17 offset:49152
	ds_read_b128 v[162:165], v17 offset:53248
	s_waitcnt lgkmcnt(10)
	v_mfma_f32_32x32x16_bf16 v[18:33], v[4:7], v[98:101], v[18:33]
	v_exp_f32_e32 v94, v94
	v_exp_f32_e32 v126, v126
	s_waitcnt lgkmcnt(8)
	v_mfma_f32_32x32x16_bf16 v[18:33], v[8:11], v[102:105], v[18:33]
	v_exp_f32_e32 v95, v95
	v_exp_f32_e32 v127, v127
	s_waitcnt lgkmcnt(6)
	v_mfma_f32_32x32x16_bf16 v[18:33], v[12:15], v[106:109], v[18:33]
	v_exp_f32_e32 v96, v96
	v_exp_f32_e32 v128, v128
	s_waitcnt lgkmcnt(4)
	v_mfma_f32_32x32x16_bf16 v[18:33], v[178:181], v[110:113], v[18:33]
	v_exp_f32_e32 v97, v97
	v_exp_f32_e32 v129, v129
	s_add_i32 s0, s86, 1
	s_cmp_lg_u32 s86, 2
	s_cselect_b32 s68, s0, 0
	s_lshl_b32 s1, s68, 14
	s_add_i32 s20, s20, 2
	s_add_i32 m0, s92, s88
	s_add_i32 s69, s1, s87
	global_load_lds_dwordx4 v[206:207], off
	v_lshl_add_u64 v[12:13], v[208:209], 0, s[26:27]
	s_cmp_le_i32 s89, s85
	s_cselect_b64 s[100:101], s[4:5], 0
	s_cbranch_scc0 .Lp2n_near2
	s_waitcnt lgkmcnt(3)
	v_mfma_f32_32x32x16_bf16 v[130:145], v[174:177], v[146:149], 0
	v_add_f32_e32 v4, v82, v83
	v_add_f32_e32 v5, v84, v85
	v_add_f32_e32 v6, v4, v5
	v_cvt_pk_bf16_f32 v4, v82, v83
	v_cvt_pk_bf16_f32 v5, v84, v85
	v_add_f32_e32 v7, v86, v87
	v_add_f32_e32 v8, v88, v89
	s_waitcnt lgkmcnt(2)
	v_mfma_f32_32x32x16_bf16 v[98:113], v[170:173], v[146:149], 0
.Lp2n_join2:
	v_add_f32_e32 v7, v7, v8
	v_add_f32_e32 v8, v7, v6
	v_cvt_pk_bf16_f32 v6, v86, v87
	v_cvt_pk_bf16_f32 v7, v88, v89
	v_add_u32_e32 v9, v182, v218
	s_mov_b32 m0, s69
	ds_read_b128 v[14:17], v9 offset:49152
	ds_read_b128 v[82:85], v9 offset:53248
	global_load_lds_dwordx4 v[12:13], off
	s_waitcnt lgkmcnt(3)
	v_mfma_f32_32x32x16_bf16 v[130:145], v[166:169], v[150:153], v[130:145]
	v_add_f32_e32 v9, v90, v91
	v_add_f32_e32 v10, v92, v93
	v_add_f32_e32 v9, v9, v10
	v_add_f32_e32 v10, v9, v8
	v_cvt_pk_bf16_f32 v8, v90, v91
	v_cvt_pk_bf16_f32 v9, v92, v93
	v_add_f32_e32 v11, v94, v95
	v_add_f32_e32 v86, v96, v97
	s_waitcnt lgkmcnt(2)
	v_mfma_f32_32x32x16_bf16 v[98:113], v[162:165], v[150:153], v[98:113]
	v_add_f32_e32 v11, v11, v86
	v_add_f32_e32 v178, v11, v10
	v_cvt_pk_bf16_f32 v10, v94, v95
	v_cvt_pk_bf16_f32 v11, v96, v97
	v_add_u32_e32 v86, v182, v219
	ds_read_b128 v[90:93], v86 offset:49152
	ds_read_b128 v[86:89], v86 offset:53248
	s_add_i32 m0, s69, 0x2000
	v_lshl_add_u64 v[12:13], v[12:13], 0, s[22:23]
	global_load_lds_dwordx4 v[12:13], off
	s_lshl_b32 s0, s91, 14
	s_waitcnt lgkmcnt(3)
	v_mfma_f32_32x32x16_bf16 v[130:145], v[14:17], v[154:157], v[130:145]
	v_add_f32_e32 v12, v114, v115
	v_add_f32_e32 v13, v116, v117
	v_add_f32_e32 v12, v12, v13
	v_add_f32_e32 v94, v12, v178
	v_cvt_pk_bf16_f32 v12, v114, v115
	v_cvt_pk_bf16_f32 v13, v116, v117
	s_waitcnt lgkmcnt(2)
	v_mfma_f32_32x32x16_bf16 v[98:113], v[82:85], v[154:157], v[98:113]
	v_add_f32_e32 v14, v118, v119
	v_add_f32_e32 v15, v120, v121
	v_add_f32_e32 v14, v14, v15
	v_add_f32_e32 v16, v14, v94
	v_cvt_pk_bf16_f32 v14, v118, v119
	v_cvt_pk_bf16_f32 v15, v120, v121
	s_waitcnt lgkmcnt(1)
	v_mfma_f32_32x32x16_bf16 v[130:145], v[90:93], v[158:161], v[130:145]
	v_add_f32_e32 v17, v122, v123
	v_add_f32_e32 v82, v124, v125
	v_add_f32_e32 v17, v17, v82
	v_add_f32_e32 v16, v17, v16
	v_cvt_pk_bf16_f32 v178, v122, v123
	v_cvt_pk_bf16_f32 v179, v124, v125
	v_add_f32_e32 v17, v126, v127
	v_add_f32_e32 v82, v128, v129
	v_add_f32_e32 v17, v17, v82
	v_add_f32_e32 v16, v17, v16
	v_cvt_pk_bf16_f32 v180, v126, v127
	v_cvt_pk_bf16_f32 v181, v128, v129
	v_add_u32_e32 v17, s0, v214
	s_waitcnt lgkmcnt(0)
	v_mfma_f32_32x32x16_bf16 v[98:113], v[86:89], v[158:161], v[98:113]
	ds_read_b64_tr_b16 v[194:195], v17
	ds_read_b64_tr_b16 v[196:197], v17 offset:256
	ds_read_b64_tr_b16 v[190:191], v17 offset:4096
	ds_read_b64_tr_b16 v[192:193], v17 offset:4352
	ds_read_b64_tr_b16 v[186:187], v17 offset:8192
	ds_read_b64_tr_b16 v[188:189], v17 offset:8448
	ds_read_b64_tr_b16 v[182:183], v17 offset:12288
	ds_read_b64_tr_b16 v[184:185], v17 offset:12544
	v_mov_b64_e32 v[82:83], v[130:131]
	s_and_b64 vcc, exec, s[100:101]
	v_mov_b64_e32 v[84:85], v[132:133]
	v_mov_b64_e32 v[86:87], v[134:135]
	v_mov_b64_e32 v[88:89], v[136:137]
	v_mov_b64_e32 v[90:91], v[138:139]
	v_mov_b64_e32 v[92:93], v[140:141]
	v_mov_b64_e32 v[94:95], v[142:143]
	v_mov_b64_e32 v[96:97], v[144:145]
	s_cbranch_vccnz .Lp2t_shift2

; #define SBAR() __builtin_amdgcn_sched_barrier(0)
; #define KRD(d0) do { if constexpr (VAR & 4) break; const char* a_ = Kc + (((2 * (d0) + hi) ^ sw) << 4); ka[d0] = *reinterpret_cast<const bf16x8*>(a_); kb[d0] = *reinterpret_cast<const bf16x8*>(a_ + 32 * 128); } while (0)
; #define VRD(i) do { if constexpr (VAR & 2) break; lo[(i) & 3] = vtr(vb + v_rd_off((i) >> 2, (i) & 3, 0)); hv[(i) & 3] = vtr(vb + v_rd_off((i) >> 2, (i) & 3, 1)); } while (0)
; #define SUM4(Y, b) do { if constexpr (!(VAR & 8)) { ps += (Y[b] + Y[(b) + 1]) + (Y[(b) + 2] + Y[(b) + 3]); asm volatile("" : "+v"(ps)); } } while (0)
; #define PKA(Y, b) do { if constexpr (!(VAR & 8)) { a0 = cvtpk(Y[b], Y[(b) + 1]); a1 = cvtpk(Y[(b) + 2], Y[(b) + 3]); } } while (0)
; #define PKB(Y, b, OUT) do { if constexpr (VAR & 8) { OUT = ka[0]; asm volatile("" : "+v"(OUT)); } else { b0 = cvtpk(Y[b], Y[(b) + 1]); b1 = cvtpk(Y[(b) + 2], Y[(b) + 3]); u32x4 w_ = {a0, a1, b0, b1}; OUT = *reinterpret_cast<bf16x8*>(&w_); asm volatile("" : "+v"(OUT)); } } while (0)
; #define QKM(X, KF, QF, C) do { if constexpr (VAR & 4) { X = C; asm volatile("" : "+v"(X)); } else X = __builtin_amdgcn_mfma_f32_32x32x16_bf16(KF, QF, C, 0, 0, 0); } while (0)
; template <int VAR> ...
;     ...
;       QKM(x0, ka[0], qr[0], z);  SUM4(y0, 0); PKA(y0, 0);       SBAR();
;       QKM(x1, kb[0], qr[0], z);  SUM4(y0, 4); PKB(y0, 4, pa0);  KRD(2); if (dv) glds16(gv, lv); SBAR(); }
;     QKM(x0, ka[1], qr[1], x0); SUM4(y0, 8); PKA(y0, 8);       SBAR();
;     QKM(x1, kb[1], qr[1], x1); SUM4(y0, 12); PKB(y0, 12, pa1); KRD(3); if (dv) glds16(gv + 8192, lv + 8192); SBAR();
;     QKM(x0, ka[2], qr[2], x0); SUM4(y1, 0); PKA(y1, 0);       SBAR();
;     QKM(x1, kb[2], qr[2], x1); SUM4(y1, 4); PKB(y1, 4, pa2);  SBAR();
;     QKM(x0, ka[3], qr[3], x0); SUM4(y1, 8); PKA(y1, 8);       SBAR();
;     QKM(x1, kb[3], qr[3], x1); SUM4(y1, 12); PKB(y1, 12, pa3); VRD(0); VRD(1); SBAR();
;     VRD(2); VRD(3); SBAR();
;     if (near) {
;         float tA[4], uA[4], tB[4], uB[4];
;     ...
;         TLD(tA, uA, 0); SBAR(); TLD(tB, uB, 1); SBAR();
;         asm volatile("s_nop 15\n\ts_nop 7" : "+v"(x0), "+v"(x1));
;         TAD(tA, uA, 0); SBAR(); TLD(tA, uA, 2); SBAR(); TAD(tB, uB, 1); SBAR(); TLD(tB, uB, 3); SBAR(); TAD(tA, uA, 2); SBAR(); TAD(tB, uB, 3);
.Lp2n_near1:
	ds_read2_b32 v[130:131], v3 offset0:123 offset1:122
	ds_read2_b32 v[132:133], v3 offset0:121 offset1:120
	ds_read2_b32 v[134:135], v3 offset0:115 offset1:114
	ds_read2_b32 v[136:137], v3 offset0:113 offset1:112
	ds_read2_b32 v[138:139], v3 offset0:107 offset1:106
	ds_read2_b32 v[140:141], v3 offset0:105 offset1:104
	ds_read2_b32 v[142:143], v3 offset0:99 offset1:98
	ds_read2_b32 v[144:145], v3 offset0:97 offset1:96
	ds_read2_b32 v[114:115], v3 offset0:91 offset1:90
	ds_read2_b32 v[116:117], v3 offset0:89 offset1:88
	ds_read2_b32 v[118:119], v3 offset0:83 offset1:82
	ds_read2_b32 v[120:121], v3 offset0:81 offset1:80
	ds_read2_b32 v[122:123], v3 offset0:75 offset1:74
	ds_read2_b32 v[124:125], v3 offset0:73 offset1:72
	ds_read2_b32 v[126:127], v3 offset0:67 offset1:66
	ds_read2_b32 v[128:129], v3 offset0:65 offset1:64
	s_waitcnt lgkmcnt(0)
	v_mfma_f32_32x32x16_bf16 v[130:145], v[174:177], v[146:149], v[130:145]
	v_add_f32_e32 v4, v82, v83
	v_add_f32_e32 v5, v84, v85
	v_add_f32_e32 v6, v4, v5
	v_cvt_pk_bf16_f32 v4, v82, v83
	v_cvt_pk_bf16_f32 v5, v84, v85
	v_add_f32_e32 v7, v86, v87
	v_add_f32_e32 v8, v88, v89
	v_mfma_f32_32x32x16_bf16 v[114:129], v[170:173], v[146:149], v[114:129]
	s_branch .Lp2n_join1
.Lp2n_near2:
	ds_read2_b32 v[130:131], v3 offset0:59 offset1:58
	ds_read2_b32 v[132:133], v3 offset0:57 offset1:56
	ds_read2_b32 v[134:135], v3 offset0:51 offset1:50
	ds_read2_b32 v[136:137], v3 offset0:49 offset1:48
	ds_read2_b32 v[138:139], v3 offset0:43 offset1:42
	ds_read2_b32 v[140:141], v3 offset0:41 offset1:40
	ds_read2_b32 v[142:143], v3 offset0:35 offset1:34
	ds_read2_b32 v[144:145], v3 offset0:33 offset1:32
	ds_read2_b32 v[98:99], v3 offset0:27 offset1:26
	ds_read2_b32 v[100:101], v3 offset0:25 offset1:24
	ds_read2_b32 v[102:103], v3 offset0:19 offset1:18
	ds_read2_b32 v[104:105], v3 offset0:17 offset1:16
	ds_read2_b32 v[106:107], v3 offset0:11 offset1:10
	ds_read2_b32 v[108:109], v3 offset0:9 offset1:8
	ds_read2_b32 v[110:111], v3 offset0:3 offset1:2
	ds_read2_b32 v[112:113], v3 offset0:1 offset1:0
	s_waitcnt lgkmcnt(0)
	v_mfma_f32_32x32x16_bf16 v[130:145], v[174:177], v[146:149], v[130:145]
	v_add_f32_e32 v4, v82, v83
	v_add_f32_e32 v5, v84, v85
	v_add_f32_e32 v6, v4, v5
	v_cvt_pk_bf16_f32 v4, v82, v83
	v_cvt_pk_bf16_f32 v5, v84, v85
	v_add_f32_e32 v7, v86, v87
	v_add_f32_e32 v8, v88, v89
	v_mfma_f32_32x32x16_bf16 v[98:113], v[170:173], v[146:149], v[98:113]
	s_branch .Lp2n_join2

; __global__ void __launch_bounds__(NWAVES * 64, 2) mega_fwd(Args args) {
;     extern __shared__ __attribute__((aligned(16))) unsigned char lds[];
	.amdhsa_kernel _Z8mega_fwd4Args
		.amdhsa_group_segment_fixed_size 0
		.amdhsa_private_segment_fixed_size 0
		.amdhsa_kernarg_size 408
		.amdhsa_user_sgpr_count 2
		.amdhsa_user_sgpr_dispatch_ptr 0
		.amdhsa_user_sgpr_queue_ptr 0
		.amdhsa_user_sgpr_kernarg_segment_ptr 1
		.amdhsa_user_sgpr_dispatch_id 0
		.amdhsa_user_sgpr_kernarg_preload_length 0
		.amdhsa_user_sgpr_kernarg_preload_offset 0
		.amdhsa_user_sgpr_private_segment_size 0
		.amdhsa_uses_dynamic_stack 0
		.amdhsa_enable_private_segment 0
		.amdhsa_system_sgpr_workgroup_id_x 1
		.amdhsa_system_sgpr_workgroup_id_y 0
		.amdhsa_system_sgpr_workgroup_id_z 0
		.amdhsa_system_sgpr_workgroup_info 0
		.amdhsa_system_vgpr_workitem_id 0
		.amdhsa_next_free_vgpr 237
		.amdhsa_next_free_sgpr 102
		.amdhsa_accum_offset 240
		.amdhsa_reserve_vcc 1
		.amdhsa_float_round_mode_32 0
		.amdhsa_float_round_mode_16_64 0
		.amdhsa_float_denorm_mode_32 3
		.amdhsa_float_denorm_mode_16_64 3
		.amdhsa_dx10_clamp 1
		.amdhsa_ieee_mode 1
		.amdhsa_fp16_overflow 0
		.amdhsa_tg_split 0
		.amdhsa_exception_fp_ieee_invalid_op 0
		.amdhsa_exception_fp_denorm_src 0
		.amdhsa_exception_fp_ieee_div_zero 0
		.amdhsa_exception_fp_ieee_overflow 0
		.amdhsa_exception_fp_ieee_underflow 0
		.amdhsa_exception_fp_ieee_inexact 0
		.amdhsa_exception_int_div_zero 0
	.end_amdhsa_kernel

; __global__ void __launch_bounds__(NWAVES * 64, 2) mega_fwd(Args args) {
;     extern __shared__ __attribute__((aligned(16))) unsigned char lds[];
amdhsa.kernels:
  - .agpr_count:     0
    .args:
      - .offset:         0
        .size:           152
        .value_kind:     by_value
      - .offset:         152
        .size:           4
        .value_kind:     hidden_block_count_x
      - .offset:         156
        .size:           4
        .value_kind:     hidden_block_count_y
      - .offset:         160
        .size:           4
        .value_kind:     hidden_block_count_z
      - .offset:         164
        .size:           2
        .value_kind:     hidden_group_size_x
      - .offset:         166
        .size:           2
        .value_kind:     hidden_group_size_y
      - .offset:         168
        .size:           2
        .value_kind:     hidden_group_size_z
      - .offset:         170
        .size:           2
        .value_kind:     hidden_remainder_x
      - .offset:         172
        .size:           2
        .value_kind:     hidden_remainder_y
      - .offset:         174
        .size:           2
        .value_kind:     hidden_remainder_z
      - .offset:         192
        .size:           8
        .value_kind:     hidden_global_offset_x
      - .offset:         200
        .size:           8
        .value_kind:     hidden_global_offset_y
      - .offset:         208
        .size:           8
        .value_kind:     hidden_global_offset_z
      - .offset:         216
        .size:           2
        .value_kind:     hidden_grid_dims
      - .offset:         272
        .size:           4
        .value_kind:     hidden_dynamic_lds_size
    .group_segment_fixed_size: 0
    .kernarg_segment_align: 8
    .kernarg_segment_size: 408
    .language:       OpenCL C
    .language_version:
      - 2
      - 0
    .max_flat_workgroup_size: 512
    .name:           _Z8mega_fwd4Args
    .private_segment_fixed_size: 0
    .sgpr_count:     108
    .sgpr_spill_count: 23
    .symbol:         _Z8mega_fwd4Args.kd
    .uniform_work_group_size: 1
    .uses_dynamic_stack: false
    .vgpr_count:     237
    .vgpr_spill_count: 0
    .wavefront_size: 64
